# half units of P1 and P3 dispatched to a dedicated 3-barrier K-loop copy (plus the half-only loops of P5 sample / P7-in-P6)
# speedup vs baseline: 1.0080x; 1.0080x over previous
.LBB0_174:
	s_ashr_i32 s71, s70, 31
	s_lshl_b64 s[50:51], s[70:71], 7
	s_add_u32 s74, s4, s50
	s_addc_u32 s75, s5, s51
	s_and_b64 s[50:51], s[46:47], exec
	s_cselect_b32 s22, s75, s1
	s_cselect_b32 s69, s74, s0
	s_ashr_i32 s73, s72, 31
	s_lshl_b64 s[50:51], s[72:73], 15
	s_add_u32 s76, s6, s50
	s_addc_u32 s77, s7, s51
	s_and_b64 s[50:51], s[46:47], exec
	v_cmp_eq_u32_e64 s[50:51], 0, v2
	v_lshl_add_u64 v[2:3], s[0:1], 0, v[222:223]
	v_lshl_add_u64 v[234:235], v[2:3], 0, v[232:233]
	v_lshl_add_u64 v[2:3], s[0:1], 0, v[224:225]
	v_mov_b32_e32 v4, v199
	v_mov_b32_e32 v5, v199
	s_cselect_b32 s71, s77, s49
	s_cselect_b32 s73, s76, s48
	v_cmp_eq_u32_e32 vcc, 0, v245
	s_add_u32 s79, s48, 0x240000
	v_lshl_add_u64 v[236:237], v[2:3], 0, v[232:233]
	v_mov_b32_e32 v2, v199
	v_mov_b32_e32 v3, v199
	v_mov_b32_e32 v66, 0
	v_mov_b64_e32 v[8:9], v[4:5]
	v_mov_b64_e32 v[20:21], v[4:5]
	v_mov_b64_e32 v[28:29], v[4:5]
	v_mov_b64_e32 v[36:37], v[4:5]
	v_mov_b64_e32 v[44:45], v[4:5]
	v_mov_b64_e32 v[52:53], v[4:5]
	v_mov_b64_e32 v[60:61], v[4:5]
	v_mov_b64_e32 v[16:17], v[4:5]
	v_mov_b64_e32 v[12:13], v[4:5]
	v_mov_b64_e32 v[32:33], v[4:5]
	v_mov_b64_e32 v[24:25], v[4:5]
	v_mov_b64_e32 v[48:49], v[4:5]
	v_mov_b64_e32 v[40:41], v[4:5]
	v_mov_b64_e32 v[64:65], v[4:5]
	v_mov_b64_e32 v[56:57], v[4:5]
	v_cndmask_b32_e32 v198, 0, v242, vcc
	s_addc_u32 s97, s49, 0
	s_mov_b32 s88, -2
	s_mov_b64 s[80:81], 0
	v_mov_b64_e32 v[6:7], v[2:3]
	v_mov_b64_e32 v[18:19], v[2:3]
	v_mov_b32_e32 v67, v66
	v_mov_b32_e32 v68, v66
	v_mov_b32_e32 v69, v66
	v_mov_b32_e32 v74, v66
	v_mov_b32_e32 v75, v66
	v_mov_b32_e32 v76, v66
	v_mov_b32_e32 v77, v66
	v_mov_b32_e32 v82, v66
	v_mov_b32_e32 v83, v66
	v_mov_b32_e32 v84, v66
	v_mov_b32_e32 v85, v66
	v_mov_b32_e32 v90, v66
	v_mov_b32_e32 v91, v66
	v_mov_b32_e32 v92, v66
	v_mov_b32_e32 v93, v66
	v_mov_b32_e32 v98, v66
	v_mov_b32_e32 v99, v66
	v_mov_b32_e32 v100, v66
	v_mov_b32_e32 v101, v66
	v_mov_b32_e32 v106, v66
	v_mov_b32_e32 v107, v66
	v_mov_b32_e32 v108, v66
	v_mov_b32_e32 v109, v66
	v_mov_b32_e32 v114, v66
	v_mov_b32_e32 v115, v66
	v_mov_b32_e32 v116, v66
	v_mov_b32_e32 v117, v66
	v_mov_b32_e32 v122, v66
	v_mov_b32_e32 v123, v66
	v_mov_b32_e32 v124, v66
	v_mov_b32_e32 v125, v66
	v_mov_b32_e32 v78, v66
	v_mov_b32_e32 v79, v66
	v_mov_b32_e32 v80, v66
	v_mov_b32_e32 v81, v66
	v_mov_b32_e32 v70, v66
	v_mov_b32_e32 v71, v66
	v_mov_b32_e32 v72, v66
	v_mov_b32_e32 v73, v66
	v_mov_b32_e32 v94, v66
	v_mov_b32_e32 v95, v66
	v_mov_b32_e32 v96, v66
	v_mov_b32_e32 v97, v66
	v_mov_b32_e32 v86, v66
	v_mov_b32_e32 v87, v66
	v_mov_b32_e32 v88, v66
	v_mov_b32_e32 v89, v66
	v_mov_b32_e32 v110, v66
	v_mov_b32_e32 v111, v66
	v_mov_b32_e32 v112, v66
	v_mov_b32_e32 v113, v66
	v_mov_b32_e32 v102, v66
	v_mov_b32_e32 v103, v66
	v_mov_b32_e32 v104, v66
	v_mov_b32_e32 v105, v66
	v_mov_b32_e32 v126, v66
	v_mov_b32_e32 v127, v66
	v_mov_b32_e32 v128, v66
	v_mov_b32_e32 v129, v66
	v_mov_b32_e32 v118, v66
	v_mov_b32_e32 v119, v66
	v_mov_b32_e32 v120, v66
	v_mov_b32_e32 v121, v66
	v_mov_b64_e32 v[26:27], v[2:3]
	v_mov_b64_e32 v[34:35], v[2:3]
	v_mov_b64_e32 v[42:43], v[2:3]
	v_mov_b64_e32 v[50:51], v[2:3]
	v_mov_b64_e32 v[58:59], v[2:3]
	v_mov_b64_e32 v[14:15], v[2:3]
	v_mov_b64_e32 v[10:11], v[2:3]
	v_mov_b64_e32 v[30:31], v[2:3]
	v_mov_b64_e32 v[22:23], v[2:3]
	v_mov_b64_e32 v[46:47], v[2:3]
	v_mov_b64_e32 v[38:39], v[2:3]
	v_mov_b64_e32 v[62:63], v[2:3]
	v_mov_b64_e32 v[54:55], v[2:3]
	s_cmp_eq_u64 s[50:51], 0
	s_cbranch_scc0 .LBB0_176
	s_mov_b32 m0, s55
	s_nop 0
	global_load_lds_dwordx4 v194, s[100:101]
	s_mov_b32 m0, s67
	s_nop 0
	global_load_lds_dwordx4 v196, s[100:101]
	s_branch .Lh0_176

.Lh0_175:
	s_add_i32 s88, s88, 2
	s_add_u32 s79, s79, 0x240000
	s_addc_u32 s97, s97, 0
	s_add_u32 s80, s80, 0x460000
	s_addc_u32 s81, s81, 0
	s_cmp_gt_u32 s88, 29
	s_cbranch_scc1 .LBB0_184
.Lh0_176:
	v_add_u32_e32 v130, 0x10000, v243
	v_add_u32_e32 v142, 0x14000, v243
	ds_read_b128 v[146:149], v130
	ds_read_b128 v[150:153], v130 offset:1024
	ds_read_b128 v[154:157], v130 offset:2048
	ds_read_b128 v[158:161], v130 offset:3072
	ds_read_b128 v[130:133], v142
	ds_read_b128 v[134:137], v142 offset:1024
	ds_read_b128 v[138:141], v142 offset:2048
	ds_read_b128 v[142:145], v142 offset:3072
	s_waitcnt lgkmcnt(0)
	ds_read_b128 v[174:177], v244
	ds_read_b128 v[190:193], v244 offset:1024
	ds_read_b128 v[170:173], v244 offset:2048
	ds_read_b128 v[186:189], v244 offset:3072
	ds_read_b128 v[166:169], v244 offset:4096
	ds_read_b128 v[182:185], v244 offset:5120
	ds_read_b128 v[162:165], v244 offset:6144
	ds_read_b128 v[178:181], v244 offset:7168
	s_waitcnt lgkmcnt(0)
	s_barrier
	v_mfma_f32_16x16x32_bf16 v[118:121], v[146:149], v[174:177], v[118:121]
	v_mfma_f32_16x16x32_bf16 v[126:129], v[154:157], v[174:177], v[126:129]
	v_mfma_f32_16x16x32_bf16 v[102:105], v[146:149], v[170:173], v[102:105]
	v_mfma_f32_16x16x32_bf16 v[110:113], v[154:157], v[170:173], v[110:113]
	v_mfma_f32_16x16x32_bf16 v[86:89], v[146:149], v[166:169], v[86:89]
	v_mfma_f32_16x16x32_bf16 v[94:97], v[154:157], v[166:169], v[94:97]
	v_mfma_f32_16x16x32_bf16 v[70:73], v[146:149], v[162:165], v[70:73]
	v_mfma_f32_16x16x32_bf16 v[78:81], v[154:157], v[162:165], v[78:81]
	v_mfma_f32_16x16x32_bf16 v[118:121], v[150:153], v[190:193], v[118:121]
	v_mfma_f32_16x16x32_bf16 v[126:129], v[158:161], v[190:193], v[126:129]
	v_mfma_f32_16x16x32_bf16 v[102:105], v[150:153], v[186:189], v[102:105]
	v_mfma_f32_16x16x32_bf16 v[110:113], v[158:161], v[186:189], v[110:113]
	v_mfma_f32_16x16x32_bf16 v[86:89], v[150:153], v[182:185], v[86:89]
	v_mfma_f32_16x16x32_bf16 v[94:97], v[158:161], v[182:185], v[94:97]
	v_mfma_f32_16x16x32_bf16 v[70:73], v[150:153], v[178:181], v[70:73]
	v_mfma_f32_16x16x32_bf16 v[78:81], v[158:161], v[178:181], v[78:81]
	v_mfma_f32_16x16x32_bf16 v[122:125], v[130:133], v[174:177], v[122:125]
	v_mfma_f32_16x16x32_bf16 v[114:117], v[138:141], v[174:177], v[114:117]
	v_mfma_f32_16x16x32_bf16 v[106:109], v[130:133], v[170:173], v[106:109]
	v_mfma_f32_16x16x32_bf16 v[98:101], v[138:141], v[170:173], v[98:101]
	v_mfma_f32_16x16x32_bf16 v[90:93], v[130:133], v[166:169], v[90:93]
	v_mfma_f32_16x16x32_bf16 v[82:85], v[138:141], v[166:169], v[82:85]
	v_mfma_f32_16x16x32_bf16 v[74:77], v[130:133], v[162:165], v[74:77]
	v_mfma_f32_16x16x32_bf16 v[66:69], v[138:141], v[162:165], v[66:69]
	v_mfma_f32_16x16x32_bf16 v[122:125], v[134:137], v[190:193], v[122:125]
	v_mfma_f32_16x16x32_bf16 v[114:117], v[142:145], v[190:193], v[114:117]
	v_mfma_f32_16x16x32_bf16 v[106:109], v[134:137], v[186:189], v[106:109]
	v_mfma_f32_16x16x32_bf16 v[98:101], v[142:145], v[186:189], v[98:101]
	v_mfma_f32_16x16x32_bf16 v[90:93], v[134:137], v[182:185], v[90:93]
	v_mfma_f32_16x16x32_bf16 v[82:85], v[142:145], v[182:185], v[82:85]
	v_mfma_f32_16x16x32_bf16 v[74:77], v[134:137], v[178:181], v[74:77]
	v_mfma_f32_16x16x32_bf16 v[66:69], v[142:145], v[178:181], v[66:69]
	s_waitcnt vmcnt(0)
	s_barrier
	s_andn2_b64 s[48:49], exec, s[50:51]
	s_andn2_b64 vcc, exec, s[50:51]
	s_cbranch_vccnz .Lh0_178
	ds_read_b128 v[174:177], v244 offset:16384
	ds_read_b128 v[190:193], v244 offset:17408
	ds_read_b128 v[170:173], v244 offset:18432
	ds_read_b128 v[186:189], v244 offset:19456
	ds_read_b128 v[166:169], v244 offset:20480
	ds_read_b128 v[182:185], v244 offset:21504
	ds_read_b128 v[162:165], v244 offset:22528
	ds_read_b128 v[178:181], v244 offset:23552
.Lh0_178:
	s_add_u32 s82, s0, s80
	s_addc_u32 s83, s1, s81
	s_add_u32 s84, s82, 0x460000
	s_addc_u32 s85, s83, 0
	s_cmp_eq_u32 s80, 0x41a0000
	s_cselect_b64 s[86:87], -1, 0
	s_and_b64 s[82:83], s[86:87], exec
	s_cselect_b32 s83, s71, s97
	s_cselect_b32 s82, s73, s79
	s_mov_b32 m0, s9
	s_cselect_b32 s85, s22, s85
	s_cselect_b32 s84, s69, s84
	s_add_u32 vcc_lo, s82, 0x4000
	global_load_lds_dwordx4 v194, s[82:83]
	s_mov_b32 m0, s10
	s_addc_u32 vcc_hi, s83, 0
	global_load_lds_dwordx4 v196, s[82:83]
	s_mov_b32 m0, s11
	s_nop 0
	global_load_lds_dwordx4 v194, vcc
	v_lshl_add_u64 v[246:247], vcc, 0, v[196:197]
	s_mov_b32 m0, s12
	s_and_b64 vcc, exec, s[48:49]
	global_load_lds_dwordx4 v[246:247], off
	s_mov_b32 m0, s8
	s_nop 0
	global_load_lds_dwordx4 v194, s[84:85]
	s_mov_b32 m0, s13
	s_nop 0
	global_load_lds_dwordx4 v196, s[84:85]
	s_waitcnt lgkmcnt(0)
	s_barrier
	s_cbranch_vccnz .Lh0_180
	s_waitcnt lgkmcnt(0)
	v_mfma_f32_16x16x32_bf16 v[54:57], v[146:149], v[174:177], v[54:57]
	v_mfma_f32_16x16x32_bf16 v[62:65], v[154:157], v[174:177], v[62:65]
	v_mfma_f32_16x16x32_bf16 v[38:41], v[146:149], v[170:173], v[38:41]
	v_mfma_f32_16x16x32_bf16 v[46:49], v[154:157], v[170:173], v[46:49]
	v_mfma_f32_16x16x32_bf16 v[22:25], v[146:149], v[166:169], v[22:25]
	v_mfma_f32_16x16x32_bf16 v[30:33], v[154:157], v[166:169], v[30:33]
	v_mfma_f32_16x16x32_bf16 v[10:13], v[146:149], v[162:165], v[10:13]
	v_mfma_f32_16x16x32_bf16 v[14:17], v[154:157], v[162:165], v[14:17]
	v_mfma_f32_16x16x32_bf16 v[54:57], v[150:153], v[190:193], v[54:57]
	v_mfma_f32_16x16x32_bf16 v[62:65], v[158:161], v[190:193], v[62:65]
	v_mfma_f32_16x16x32_bf16 v[38:41], v[150:153], v[186:189], v[38:41]
	v_mfma_f32_16x16x32_bf16 v[46:49], v[158:161], v[186:189], v[46:49]
	v_mfma_f32_16x16x32_bf16 v[22:25], v[150:153], v[182:185], v[22:25]
	v_mfma_f32_16x16x32_bf16 v[30:33], v[158:161], v[182:185], v[30:33]
	v_mfma_f32_16x16x32_bf16 v[10:13], v[150:153], v[178:181], v[10:13]
	v_mfma_f32_16x16x32_bf16 v[14:17], v[158:161], v[178:181], v[14:17]
	v_mfma_f32_16x16x32_bf16 v[58:61], v[130:133], v[174:177], v[58:61]
	v_mfma_f32_16x16x32_bf16 v[50:53], v[138:141], v[174:177], v[50:53]
	v_mfma_f32_16x16x32_bf16 v[42:45], v[130:133], v[170:173], v[42:45]
	v_mfma_f32_16x16x32_bf16 v[34:37], v[138:141], v[170:173], v[34:37]
	v_mfma_f32_16x16x32_bf16 v[26:29], v[130:133], v[166:169], v[26:29]
	v_mfma_f32_16x16x32_bf16 v[18:21], v[138:141], v[166:169], v[18:21]
	v_mfma_f32_16x16x32_bf16 v[6:9], v[130:133], v[162:165], v[6:9]
	v_mfma_f32_16x16x32_bf16 v[2:5], v[138:141], v[162:165], v[2:5]
	v_mfma_f32_16x16x32_bf16 v[58:61], v[134:137], v[190:193], v[58:61]
	v_mfma_f32_16x16x32_bf16 v[50:53], v[142:145], v[190:193], v[50:53]
	v_mfma_f32_16x16x32_bf16 v[42:45], v[134:137], v[186:189], v[42:45]
	v_mfma_f32_16x16x32_bf16 v[34:37], v[142:145], v[186:189], v[34:37]
	v_mfma_f32_16x16x32_bf16 v[26:29], v[134:137], v[182:185], v[26:29]
	v_mfma_f32_16x16x32_bf16 v[18:21], v[142:145], v[182:185], v[18:21]
	v_mfma_f32_16x16x32_bf16 v[6:9], v[134:137], v[178:181], v[6:9]
	v_mfma_f32_16x16x32_bf16 v[2:5], v[142:145], v[178:181], v[2:5]
.Lh0_180:
	s_and_b64 vcc, s[46:47], s[86:87]
	v_cndmask_b32_e64 v131, v233, 0, vcc
	v_cndmask_b32_e32 v130, v232, v198, vcc
	v_lshl_add_u64 v[246:247], s[84:85], 0, v[130:131]
	v_add_u32_e32 v130, 0x18000, v243
	v_add_u32_e32 v142, 0x1c000, v243
	ds_read_b128 v[146:149], v130
	ds_read_b128 v[150:153], v130 offset:1024
	ds_read_b128 v[154:157], v130 offset:2048
	ds_read_b128 v[158:161], v130 offset:3072
	ds_read_b128 v[130:133], v142
	ds_read_b128 v[134:137], v142 offset:1024
	ds_read_b128 v[138:141], v142 offset:2048
	ds_read_b128 v[142:145], v142 offset:3072
	s_waitcnt lgkmcnt(0)
	ds_read_b128 v[174:177], v244 offset:32768
	ds_read_b128 v[190:193], v244 offset:33792
	ds_read_b128 v[170:173], v244 offset:34816
	ds_read_b128 v[186:189], v244 offset:35840
	ds_read_b128 v[166:169], v244 offset:36864
	ds_read_b128 v[182:185], v244 offset:37888
	ds_read_b128 v[162:165], v244 offset:38912
	ds_read_b128 v[178:181], v244 offset:39936
	s_waitcnt lgkmcnt(0)
	s_barrier
	v_mfma_f32_16x16x32_bf16 v[118:121], v[146:149], v[174:177], v[118:121]
	v_mfma_f32_16x16x32_bf16 v[126:129], v[154:157], v[174:177], v[126:129]
	v_mfma_f32_16x16x32_bf16 v[102:105], v[146:149], v[170:173], v[102:105]
	v_mfma_f32_16x16x32_bf16 v[110:113], v[154:157], v[170:173], v[110:113]
	v_mfma_f32_16x16x32_bf16 v[86:89], v[146:149], v[166:169], v[86:89]
	v_mfma_f32_16x16x32_bf16 v[94:97], v[154:157], v[166:169], v[94:97]
	v_mfma_f32_16x16x32_bf16 v[70:73], v[146:149], v[162:165], v[70:73]
	v_mfma_f32_16x16x32_bf16 v[78:81], v[154:157], v[162:165], v[78:81]
	v_mfma_f32_16x16x32_bf16 v[118:121], v[150:153], v[190:193], v[118:121]
	v_mfma_f32_16x16x32_bf16 v[126:129], v[158:161], v[190:193], v[126:129]
	v_mfma_f32_16x16x32_bf16 v[102:105], v[150:153], v[186:189], v[102:105]
	v_mfma_f32_16x16x32_bf16 v[110:113], v[158:161], v[186:189], v[110:113]
	v_mfma_f32_16x16x32_bf16 v[86:89], v[150:153], v[182:185], v[86:89]
	v_mfma_f32_16x16x32_bf16 v[94:97], v[158:161], v[182:185], v[94:97]
	v_mfma_f32_16x16x32_bf16 v[70:73], v[150:153], v[178:181], v[70:73]
	v_mfma_f32_16x16x32_bf16 v[78:81], v[158:161], v[178:181], v[78:81]
	v_mfma_f32_16x16x32_bf16 v[122:125], v[130:133], v[174:177], v[122:125]
	v_mfma_f32_16x16x32_bf16 v[114:117], v[138:141], v[174:177], v[114:117]
	v_mfma_f32_16x16x32_bf16 v[106:109], v[130:133], v[170:173], v[106:109]
	v_mfma_f32_16x16x32_bf16 v[98:101], v[138:141], v[170:173], v[98:101]
	v_mfma_f32_16x16x32_bf16 v[90:93], v[130:133], v[166:169], v[90:93]
	v_mfma_f32_16x16x32_bf16 v[82:85], v[138:141], v[166:169], v[82:85]
	v_mfma_f32_16x16x32_bf16 v[74:77], v[130:133], v[162:165], v[74:77]
	v_mfma_f32_16x16x32_bf16 v[66:69], v[138:141], v[162:165], v[66:69]
	v_mfma_f32_16x16x32_bf16 v[122:125], v[134:137], v[190:193], v[122:125]
	v_mfma_f32_16x16x32_bf16 v[114:117], v[142:145], v[190:193], v[114:117]
	v_mfma_f32_16x16x32_bf16 v[106:109], v[134:137], v[186:189], v[106:109]
	v_mfma_f32_16x16x32_bf16 v[98:101], v[142:145], v[186:189], v[98:101]
	v_mfma_f32_16x16x32_bf16 v[90:93], v[134:137], v[182:185], v[90:93]
	v_mfma_f32_16x16x32_bf16 v[82:85], v[142:145], v[182:185], v[82:85]
	v_mfma_f32_16x16x32_bf16 v[74:77], v[134:137], v[178:181], v[74:77]
	v_mfma_f32_16x16x32_bf16 v[66:69], v[142:145], v[178:181], v[66:69]
	s_waitcnt vmcnt(0)
	s_barrier
	s_and_b64 vcc, exec, s[48:49]
	s_cbranch_vccnz .Lh0_182
	ds_read_b128 v[174:177], v244 offset:49152
	ds_read_b128 v[190:193], v244 offset:50176
	ds_read_b128 v[170:173], v244 offset:51200
	ds_read_b128 v[186:189], v244 offset:52224
	ds_read_b128 v[166:169], v244 offset:53248
	ds_read_b128 v[182:185], v244 offset:54272
	ds_read_b128 v[162:165], v244 offset:55296
	ds_read_b128 v[178:181], v244 offset:56320
.Lh0_182:
	s_add_u32 s86, s82, 0x120000
	s_addc_u32 s87, s83, 0
	s_add_u32 s84, s84, 0x230000
	s_addc_u32 s85, s85, 0
	s_mov_b32 m0, s17
	s_add_u32 s82, s82, 0x124000
	global_load_lds_dwordx4 v194, s[86:87]
	s_mov_b32 m0, s54
	s_addc_u32 s83, s83, 0
	global_load_lds_dwordx4 v196, s[86:87]
	s_mov_b32 m0, s89
	s_and_b64 vcc, exec, s[48:49]
	global_load_lds_dwordx4 v194, s[82:83]
	s_mov_b32 m0, s90
	s_nop 0
	global_load_lds_dwordx4 v196, s[82:83]
	s_mov_b32 m0, s55
	s_nop 0
	global_load_lds_dwordx4 v194, s[84:85]
	s_mov_b32 m0, s67
	s_nop 0
	global_load_lds_dwordx4 v196, s[84:85]
	s_waitcnt lgkmcnt(0)
	s_barrier
	s_cbranch_vccnz .Lh0_175
	s_waitcnt lgkmcnt(0)
	v_mfma_f32_16x16x32_bf16 v[54:57], v[146:149], v[174:177], v[54:57]
	v_mfma_f32_16x16x32_bf16 v[62:65], v[154:157], v[174:177], v[62:65]
	v_mfma_f32_16x16x32_bf16 v[38:41], v[146:149], v[170:173], v[38:41]
	v_mfma_f32_16x16x32_bf16 v[46:49], v[154:157], v[170:173], v[46:49]
	v_mfma_f32_16x16x32_bf16 v[22:25], v[146:149], v[166:169], v[22:25]
	v_mfma_f32_16x16x32_bf16 v[30:33], v[154:157], v[166:169], v[30:33]
	v_mfma_f32_16x16x32_bf16 v[10:13], v[146:149], v[162:165], v[10:13]
	v_mfma_f32_16x16x32_bf16 v[14:17], v[154:157], v[162:165], v[14:17]
	v_mfma_f32_16x16x32_bf16 v[54:57], v[150:153], v[190:193], v[54:57]
	v_mfma_f32_16x16x32_bf16 v[62:65], v[158:161], v[190:193], v[62:65]
	v_mfma_f32_16x16x32_bf16 v[38:41], v[150:153], v[186:189], v[38:41]
	v_mfma_f32_16x16x32_bf16 v[46:49], v[158:161], v[186:189], v[46:49]
	v_mfma_f32_16x16x32_bf16 v[22:25], v[150:153], v[182:185], v[22:25]
	v_mfma_f32_16x16x32_bf16 v[30:33], v[158:161], v[182:185], v[30:33]
	v_mfma_f32_16x16x32_bf16 v[10:13], v[150:153], v[178:181], v[10:13]
	v_mfma_f32_16x16x32_bf16 v[14:17], v[158:161], v[178:181], v[14:17]
	v_mfma_f32_16x16x32_bf16 v[58:61], v[130:133], v[174:177], v[58:61]
	v_mfma_f32_16x16x32_bf16 v[50:53], v[138:141], v[174:177], v[50:53]
	v_mfma_f32_16x16x32_bf16 v[42:45], v[130:133], v[170:173], v[42:45]
	v_mfma_f32_16x16x32_bf16 v[34:37], v[138:141], v[170:173], v[34:37]
	v_mfma_f32_16x16x32_bf16 v[26:29], v[130:133], v[166:169], v[26:29]
	v_mfma_f32_16x16x32_bf16 v[18:21], v[138:141], v[166:169], v[18:21]
	v_mfma_f32_16x16x32_bf16 v[6:9], v[130:133], v[162:165], v[6:9]
	v_mfma_f32_16x16x32_bf16 v[2:5], v[138:141], v[162:165], v[2:5]
	v_mfma_f32_16x16x32_bf16 v[58:61], v[134:137], v[190:193], v[58:61]
	v_mfma_f32_16x16x32_bf16 v[50:53], v[142:145], v[190:193], v[50:53]
	v_mfma_f32_16x16x32_bf16 v[42:45], v[134:137], v[186:189], v[42:45]
	v_mfma_f32_16x16x32_bf16 v[34:37], v[142:145], v[186:189], v[34:37]
	v_mfma_f32_16x16x32_bf16 v[26:29], v[134:137], v[182:185], v[26:29]
	v_mfma_f32_16x16x32_bf16 v[18:21], v[142:145], v[182:185], v[18:21]
	v_mfma_f32_16x16x32_bf16 v[6:9], v[134:137], v[178:181], v[6:9]
	v_mfma_f32_16x16x32_bf16 v[2:5], v[142:145], v[178:181], v[2:5]
	s_setprio 0
	s_branch .Lh0_175

.LBB0_557:
	s_ashr_i32 s37, s36, 31
	s_lshl_b64 s[42:43], s[36:37], 7
	s_add_u32 s48, s4, s42
	s_addc_u32 s49, s5, s43
	s_and_b64 s[42:43], s[40:41], exec
	s_cselect_b32 s1, s49, s57
	s_cselect_b32 s24, s48, s56
	s_ashr_i32 s47, s46, 31
	s_lshl_b64 s[42:43], s[46:47], 15
	s_add_u32 s50, s6, s42
	s_addc_u32 s51, s7, s43
	s_and_b64 s[42:43], s[40:41], exec
	s_waitcnt lgkmcnt(0)
	v_lshl_add_u64 v[2:3], s[56:57], 0, v[204:205]
	s_cselect_b32 s37, s51, s45
	s_cselect_b32 s47, s50, s44
	s_add_u32 s53, s44, 0x80000
	v_lshl_add_u64 v[216:217], v[2:3], 0, v[214:215]
	v_lshl_add_u64 v[2:3], s[56:57], 0, v[206:207]
	v_mov_b32_e32 v4, v199
	v_mov_b32_e32 v5, v199
	v_cmp_eq_u32_e32 vcc, 0, v232
	s_addc_u32 s72, s45, 0
	v_lshl_add_u64 v[218:219], v[2:3], 0, v[214:215]
	v_mov_b32_e32 v2, v199
	v_mov_b32_e32 v3, v199
	v_mov_b32_e32 v66, 0
	v_cmp_eq_u32_e64 s[44:45], 0, v6
	v_mov_b64_e32 v[8:9], v[4:5]
	v_mov_b64_e32 v[20:21], v[4:5]
	v_mov_b64_e32 v[24:25], v[4:5]
	v_mov_b64_e32 v[36:37], v[4:5]
	v_mov_b64_e32 v[40:41], v[4:5]
	v_mov_b64_e32 v[52:53], v[4:5]
	v_mov_b64_e32 v[56:57], v[4:5]
	v_mov_b64_e32 v[12:13], v[4:5]
	v_mov_b64_e32 v[16:17], v[4:5]
	v_mov_b64_e32 v[28:29], v[4:5]
	v_mov_b64_e32 v[32:33], v[4:5]
	v_mov_b64_e32 v[44:45], v[4:5]
	v_mov_b64_e32 v[48:49], v[4:5]
	v_mov_b64_e32 v[60:61], v[4:5]
	v_mov_b64_e32 v[64:65], v[4:5]
	v_cndmask_b32_e32 v198, 0, v225, vcc
	s_mov_b32 s73, -2
	s_mov_b64 s[58:59], 0
	v_cndmask_b32_e64 v233, 0, 1, s[44:45]
	v_mov_b64_e32 v[6:7], v[2:3]
	v_mov_b64_e32 v[18:19], v[2:3]
	v_mov_b64_e32 v[22:23], v[2:3]
	v_mov_b64_e32 v[34:35], v[2:3]
	v_mov_b64_e32 v[38:39], v[2:3]
	v_mov_b64_e32 v[50:51], v[2:3]
	v_mov_b64_e32 v[54:55], v[2:3]
	v_mov_b64_e32 v[10:11], v[2:3]
	v_mov_b64_e32 v[14:15], v[2:3]
	v_mov_b64_e32 v[26:27], v[2:3]
	v_mov_b64_e32 v[30:31], v[2:3]
	v_mov_b64_e32 v[42:43], v[2:3]
	v_mov_b64_e32 v[46:47], v[2:3]
	v_mov_b64_e32 v[58:59], v[2:3]
	v_mov_b64_e32 v[62:63], v[2:3]
	v_mov_b32_e32 v67, v66
	v_mov_b32_e32 v68, v66
	v_mov_b32_e32 v69, v66
	v_mov_b32_e32 v70, v66
	v_mov_b32_e32 v71, v66
	v_mov_b32_e32 v72, v66
	v_mov_b32_e32 v73, v66
	v_mov_b32_e32 v82, v66
	v_mov_b32_e32 v83, v66
	v_mov_b32_e32 v84, v66
	v_mov_b32_e32 v85, v66
	v_mov_b32_e32 v86, v66
	v_mov_b32_e32 v87, v66
	v_mov_b32_e32 v88, v66
	v_mov_b32_e32 v89, v66
	v_mov_b32_e32 v98, v66
	v_mov_b32_e32 v99, v66
	v_mov_b32_e32 v100, v66
	v_mov_b32_e32 v101, v66
	v_mov_b32_e32 v102, v66
	v_mov_b32_e32 v103, v66
	v_mov_b32_e32 v104, v66
	v_mov_b32_e32 v105, v66
	v_mov_b32_e32 v114, v66
	v_mov_b32_e32 v115, v66
	v_mov_b32_e32 v116, v66
	v_mov_b32_e32 v117, v66
	v_mov_b32_e32 v118, v66
	v_mov_b32_e32 v119, v66
	v_mov_b32_e32 v120, v66
	v_mov_b32_e32 v121, v66
	v_mov_b32_e32 v74, v66
	v_mov_b32_e32 v75, v66
	v_mov_b32_e32 v76, v66
	v_mov_b32_e32 v77, v66
	v_mov_b32_e32 v78, v66
	v_mov_b32_e32 v79, v66
	v_mov_b32_e32 v80, v66
	v_mov_b32_e32 v81, v66
	v_mov_b32_e32 v90, v66
	v_mov_b32_e32 v91, v66
	v_mov_b32_e32 v92, v66
	v_mov_b32_e32 v93, v66
	v_mov_b32_e32 v94, v66
	v_mov_b32_e32 v95, v66
	v_mov_b32_e32 v96, v66
	v_mov_b32_e32 v97, v66
	v_mov_b32_e32 v106, v66
	v_mov_b32_e32 v107, v66
	v_mov_b32_e32 v108, v66
	v_mov_b32_e32 v109, v66
	v_mov_b32_e32 v110, v66
	v_mov_b32_e32 v111, v66
	v_mov_b32_e32 v112, v66
	v_mov_b32_e32 v113, v66
	v_mov_b32_e32 v122, v66
	v_mov_b32_e32 v123, v66
	v_mov_b32_e32 v124, v66
	v_mov_b32_e32 v125, v66
	v_mov_b32_e32 v126, v66
	v_mov_b32_e32 v127, v66
	v_mov_b32_e32 v128, v66
	v_mov_b32_e32 v129, v66
	s_waitcnt vmcnt(0)
	s_cmp_eq_u64 s[44:45], 0
	s_cbranch_scc0 .LBB0_559
	s_mov_b32 m0, s55
	s_nop 0
	global_load_lds_dwordx4 v194, s[100:101]
	s_mov_b32 m0, s67
	s_nop 0
	global_load_lds_dwordx4 v196, s[100:101]
	s_branch .Lh1_559

.Lh1_558:
	s_add_i32 s73, s73, 2
	s_add_u32 s53, s53, 0x80000
	s_addc_u32 s72, s72, 0
	s_add_u32 s58, s58, 0x440000
	s_addc_u32 s59, s59, 0
	s_cmp_gt_u32 s73, 29
	s_cbranch_scc1 .LBB0_567
.Lh1_559:
	ds_read_b128 v[146:149], v227
	ds_read_b128 v[150:153], v227 offset:1024
	ds_read_b128 v[154:157], v227 offset:2048
	ds_read_b128 v[158:161], v227 offset:3072
	ds_read_b128 v[130:133], v228
	ds_read_b128 v[134:137], v228 offset:1024
	ds_read_b128 v[138:141], v228 offset:2048
	ds_read_b128 v[142:145], v228 offset:3072
	s_waitcnt lgkmcnt(0)
	ds_read_b128 v[174:177], v229
	ds_read_b128 v[190:193], v229 offset:1024
	ds_read_b128 v[170:173], v229 offset:2048
	ds_read_b128 v[186:189], v229 offset:3072
	ds_read_b128 v[166:169], v229 offset:4096
	ds_read_b128 v[182:185], v229 offset:5120
	ds_read_b128 v[162:165], v229 offset:6144
	ds_read_b128 v[178:181], v229 offset:7168
	s_waitcnt lgkmcnt(0)
	s_barrier
	v_mfma_f32_16x16x32_bf16 v[126:129], v[146:149], v[174:177], v[126:129]
	v_mfma_f32_16x16x32_bf16 v[122:125], v[154:157], v[174:177], v[122:125]
	v_mfma_f32_16x16x32_bf16 v[110:113], v[146:149], v[170:173], v[110:113]
	v_mfma_f32_16x16x32_bf16 v[106:109], v[154:157], v[170:173], v[106:109]
	v_mfma_f32_16x16x32_bf16 v[94:97], v[146:149], v[166:169], v[94:97]
	v_mfma_f32_16x16x32_bf16 v[90:93], v[154:157], v[166:169], v[90:93]
	v_mfma_f32_16x16x32_bf16 v[78:81], v[146:149], v[162:165], v[78:81]
	v_mfma_f32_16x16x32_bf16 v[74:77], v[154:157], v[162:165], v[74:77]
	v_mfma_f32_16x16x32_bf16 v[126:129], v[150:153], v[190:193], v[126:129]
	v_mfma_f32_16x16x32_bf16 v[122:125], v[158:161], v[190:193], v[122:125]
	v_mfma_f32_16x16x32_bf16 v[110:113], v[150:153], v[186:189], v[110:113]
	v_mfma_f32_16x16x32_bf16 v[106:109], v[158:161], v[186:189], v[106:109]
	v_mfma_f32_16x16x32_bf16 v[94:97], v[150:153], v[182:185], v[94:97]
	v_mfma_f32_16x16x32_bf16 v[90:93], v[158:161], v[182:185], v[90:93]
	v_mfma_f32_16x16x32_bf16 v[78:81], v[150:153], v[178:181], v[78:81]
	v_mfma_f32_16x16x32_bf16 v[74:77], v[158:161], v[178:181], v[74:77]
	v_mfma_f32_16x16x32_bf16 v[118:121], v[130:133], v[174:177], v[118:121]
	v_mfma_f32_16x16x32_bf16 v[114:117], v[138:141], v[174:177], v[114:117]
	v_mfma_f32_16x16x32_bf16 v[102:105], v[130:133], v[170:173], v[102:105]
	v_mfma_f32_16x16x32_bf16 v[98:101], v[138:141], v[170:173], v[98:101]
	v_mfma_f32_16x16x32_bf16 v[86:89], v[130:133], v[166:169], v[86:89]
	v_mfma_f32_16x16x32_bf16 v[82:85], v[138:141], v[166:169], v[82:85]
	v_mfma_f32_16x16x32_bf16 v[70:73], v[130:133], v[162:165], v[70:73]
	v_mfma_f32_16x16x32_bf16 v[66:69], v[138:141], v[162:165], v[66:69]
	v_mfma_f32_16x16x32_bf16 v[118:121], v[134:137], v[190:193], v[118:121]
	v_mfma_f32_16x16x32_bf16 v[114:117], v[142:145], v[190:193], v[114:117]
	v_mfma_f32_16x16x32_bf16 v[102:105], v[134:137], v[186:189], v[102:105]
	v_mfma_f32_16x16x32_bf16 v[98:101], v[142:145], v[186:189], v[98:101]
	v_mfma_f32_16x16x32_bf16 v[86:89], v[134:137], v[182:185], v[86:89]
	v_mfma_f32_16x16x32_bf16 v[82:85], v[142:145], v[182:185], v[82:85]
	v_mfma_f32_16x16x32_bf16 v[70:73], v[134:137], v[178:181], v[70:73]
	v_mfma_f32_16x16x32_bf16 v[66:69], v[142:145], v[178:181], v[66:69]
	s_waitcnt vmcnt(0)
	s_barrier
	v_cmp_ne_u32_e64 s[42:43], 1, v233
	s_andn2_b64 vcc, exec, s[44:45]
	s_cbranch_vccnz .Lh1_561
	ds_read_b128 v[174:177], v229 offset:16384
	ds_read_b128 v[190:193], v229 offset:17408
	ds_read_b128 v[170:173], v229 offset:18432
	ds_read_b128 v[186:189], v229 offset:19456
	ds_read_b128 v[166:169], v229 offset:20480
	ds_read_b128 v[182:185], v229 offset:21504
	ds_read_b128 v[162:165], v229 offset:22528
	ds_read_b128 v[178:181], v229 offset:23552
.Lh1_561:
	s_add_u32 s60, s56, s58
	s_addc_u32 s61, s57, s59
	s_add_u32 s62, s60, 0x440000
	s_addc_u32 s63, s61, 0
	s_cmp_eq_u32 s58, 0x3fc0000
	s_cselect_b64 s[68:69], -1, 0
	s_and_b64 s[60:61], s[68:69], exec
	s_cselect_b32 s61, s37, s72
	s_cselect_b32 s60, s47, s53
	s_mov_b32 m0, s9
	s_cselect_b32 s63, s1, s63
	s_cselect_b32 s62, s24, s62
	s_add_u32 s74, s60, 0x4000
	global_load_lds_dwordx4 v194, s[60:61]
	s_mov_b32 m0, s10
	s_addc_u32 s75, s61, 0
	global_load_lds_dwordx4 v196, s[60:61]
	s_mov_b32 m0, s11
	s_and_b64 vcc, exec, s[42:43]
	global_load_lds_dwordx4 v194, s[74:75]
	s_mov_b32 m0, s12
	s_nop 0
	global_load_lds_dwordx4 v196, s[74:75]
	s_mov_b32 m0, s8
	s_nop 0
	global_load_lds_dwordx4 v194, s[62:63]
	s_mov_b32 m0, s13
	s_nop 0
	global_load_lds_dwordx4 v196, s[62:63]
	s_waitcnt lgkmcnt(0)
	s_barrier
	s_cbranch_vccnz .Lh1_563
	s_waitcnt lgkmcnt(0)
	v_mfma_f32_16x16x32_bf16 v[62:65], v[146:149], v[174:177], v[62:65]
	v_mfma_f32_16x16x32_bf16 v[58:61], v[154:157], v[174:177], v[58:61]
	v_mfma_f32_16x16x32_bf16 v[46:49], v[146:149], v[170:173], v[46:49]
	v_mfma_f32_16x16x32_bf16 v[42:45], v[154:157], v[170:173], v[42:45]
	v_mfma_f32_16x16x32_bf16 v[30:33], v[146:149], v[166:169], v[30:33]
	v_mfma_f32_16x16x32_bf16 v[26:29], v[154:157], v[166:169], v[26:29]
	v_mfma_f32_16x16x32_bf16 v[14:17], v[146:149], v[162:165], v[14:17]
	v_mfma_f32_16x16x32_bf16 v[10:13], v[154:157], v[162:165], v[10:13]
	v_mfma_f32_16x16x32_bf16 v[62:65], v[150:153], v[190:193], v[62:65]
	v_mfma_f32_16x16x32_bf16 v[58:61], v[158:161], v[190:193], v[58:61]
	v_mfma_f32_16x16x32_bf16 v[46:49], v[150:153], v[186:189], v[46:49]
	v_mfma_f32_16x16x32_bf16 v[42:45], v[158:161], v[186:189], v[42:45]
	v_mfma_f32_16x16x32_bf16 v[30:33], v[150:153], v[182:185], v[30:33]
	v_mfma_f32_16x16x32_bf16 v[26:29], v[158:161], v[182:185], v[26:29]
	v_mfma_f32_16x16x32_bf16 v[14:17], v[150:153], v[178:181], v[14:17]
	v_mfma_f32_16x16x32_bf16 v[10:13], v[158:161], v[178:181], v[10:13]
	v_mfma_f32_16x16x32_bf16 v[54:57], v[130:133], v[174:177], v[54:57]
	v_mfma_f32_16x16x32_bf16 v[50:53], v[138:141], v[174:177], v[50:53]
	v_mfma_f32_16x16x32_bf16 v[38:41], v[130:133], v[170:173], v[38:41]
	v_mfma_f32_16x16x32_bf16 v[34:37], v[138:141], v[170:173], v[34:37]
	v_mfma_f32_16x16x32_bf16 v[22:25], v[130:133], v[166:169], v[22:25]
	v_mfma_f32_16x16x32_bf16 v[18:21], v[138:141], v[166:169], v[18:21]
	v_mfma_f32_16x16x32_bf16 v[6:9], v[130:133], v[162:165], v[6:9]
	v_mfma_f32_16x16x32_bf16 v[2:5], v[138:141], v[162:165], v[2:5]
	v_mfma_f32_16x16x32_bf16 v[54:57], v[134:137], v[190:193], v[54:57]
	v_mfma_f32_16x16x32_bf16 v[50:53], v[142:145], v[190:193], v[50:53]
	v_mfma_f32_16x16x32_bf16 v[38:41], v[134:137], v[186:189], v[38:41]
	v_mfma_f32_16x16x32_bf16 v[34:37], v[142:145], v[186:189], v[34:37]
	v_mfma_f32_16x16x32_bf16 v[22:25], v[134:137], v[182:185], v[22:25]
	v_mfma_f32_16x16x32_bf16 v[18:21], v[142:145], v[182:185], v[18:21]
	v_mfma_f32_16x16x32_bf16 v[6:9], v[134:137], v[178:181], v[6:9]
	v_mfma_f32_16x16x32_bf16 v[2:5], v[142:145], v[178:181], v[2:5]
.Lh1_563:
	s_and_b64 vcc, s[40:41], s[68:69]
	v_cndmask_b32_e64 v131, v215, 0, vcc
	v_cndmask_b32_e32 v130, v214, v198, vcc
	v_lshl_add_u64 v[234:235], s[62:63], 0, v[130:131]
	v_add_u32_e32 v130, 0x18000, v226
	v_add_u32_e32 v142, 0x1c000, v226
	ds_read_b128 v[146:149], v130
	ds_read_b128 v[150:153], v130 offset:1024
	ds_read_b128 v[154:157], v130 offset:2048
	ds_read_b128 v[158:161], v130 offset:3072
	ds_read_b128 v[130:133], v142
	ds_read_b128 v[134:137], v142 offset:1024
	ds_read_b128 v[138:141], v142 offset:2048
	ds_read_b128 v[142:145], v142 offset:3072
	s_waitcnt lgkmcnt(0)
	ds_read_b128 v[174:177], v229 offset:32768
	ds_read_b128 v[190:193], v229 offset:33792
	ds_read_b128 v[170:173], v229 offset:34816
	ds_read_b128 v[186:189], v229 offset:35840
	ds_read_b128 v[166:169], v229 offset:36864
	ds_read_b128 v[182:185], v229 offset:37888
	ds_read_b128 v[162:165], v229 offset:38912
	ds_read_b128 v[178:181], v229 offset:39936
	s_waitcnt lgkmcnt(0)
	s_barrier
	v_mfma_f32_16x16x32_bf16 v[126:129], v[146:149], v[174:177], v[126:129]
	v_mfma_f32_16x16x32_bf16 v[122:125], v[154:157], v[174:177], v[122:125]
	v_mfma_f32_16x16x32_bf16 v[110:113], v[146:149], v[170:173], v[110:113]
	v_mfma_f32_16x16x32_bf16 v[106:109], v[154:157], v[170:173], v[106:109]
	v_mfma_f32_16x16x32_bf16 v[94:97], v[146:149], v[166:169], v[94:97]
	v_mfma_f32_16x16x32_bf16 v[90:93], v[154:157], v[166:169], v[90:93]
	v_mfma_f32_16x16x32_bf16 v[78:81], v[146:149], v[162:165], v[78:81]
	v_mfma_f32_16x16x32_bf16 v[74:77], v[154:157], v[162:165], v[74:77]
	v_mfma_f32_16x16x32_bf16 v[126:129], v[150:153], v[190:193], v[126:129]
	v_mfma_f32_16x16x32_bf16 v[122:125], v[158:161], v[190:193], v[122:125]
	v_mfma_f32_16x16x32_bf16 v[110:113], v[150:153], v[186:189], v[110:113]
	v_mfma_f32_16x16x32_bf16 v[106:109], v[158:161], v[186:189], v[106:109]
	v_mfma_f32_16x16x32_bf16 v[94:97], v[150:153], v[182:185], v[94:97]
	v_mfma_f32_16x16x32_bf16 v[90:93], v[158:161], v[182:185], v[90:93]
	v_mfma_f32_16x16x32_bf16 v[78:81], v[150:153], v[178:181], v[78:81]
	v_mfma_f32_16x16x32_bf16 v[74:77], v[158:161], v[178:181], v[74:77]
	v_mfma_f32_16x16x32_bf16 v[118:121], v[130:133], v[174:177], v[118:121]
	v_mfma_f32_16x16x32_bf16 v[114:117], v[138:141], v[174:177], v[114:117]
	v_mfma_f32_16x16x32_bf16 v[102:105], v[130:133], v[170:173], v[102:105]
	v_mfma_f32_16x16x32_bf16 v[98:101], v[138:141], v[170:173], v[98:101]
	v_mfma_f32_16x16x32_bf16 v[86:89], v[130:133], v[166:169], v[86:89]
	v_mfma_f32_16x16x32_bf16 v[82:85], v[138:141], v[166:169], v[82:85]
	v_mfma_f32_16x16x32_bf16 v[70:73], v[130:133], v[162:165], v[70:73]
	v_mfma_f32_16x16x32_bf16 v[66:69], v[138:141], v[162:165], v[66:69]
	v_mfma_f32_16x16x32_bf16 v[118:121], v[134:137], v[190:193], v[118:121]
	v_mfma_f32_16x16x32_bf16 v[114:117], v[142:145], v[190:193], v[114:117]
	v_mfma_f32_16x16x32_bf16 v[102:105], v[134:137], v[186:189], v[102:105]
	v_mfma_f32_16x16x32_bf16 v[98:101], v[142:145], v[186:189], v[98:101]
	v_mfma_f32_16x16x32_bf16 v[86:89], v[134:137], v[182:185], v[86:89]
	v_mfma_f32_16x16x32_bf16 v[82:85], v[142:145], v[182:185], v[82:85]
	v_mfma_f32_16x16x32_bf16 v[70:73], v[134:137], v[178:181], v[70:73]
	v_mfma_f32_16x16x32_bf16 v[66:69], v[142:145], v[178:181], v[66:69]
	s_waitcnt vmcnt(0)
	s_barrier
	s_and_b64 vcc, exec, s[42:43]
	s_cbranch_vccnz .Lh1_565
	ds_read_b128 v[174:177], v229 offset:49152
	ds_read_b128 v[190:193], v229 offset:50176
	ds_read_b128 v[170:173], v229 offset:51200
	ds_read_b128 v[186:189], v229 offset:52224
	ds_read_b128 v[166:169], v229 offset:53248
	ds_read_b128 v[182:185], v229 offset:54272
	ds_read_b128 v[162:165], v229 offset:55296
	ds_read_b128 v[178:181], v229 offset:56320
.Lh1_565:
	s_add_u32 s68, s60, 0x40000
	s_addc_u32 s69, s61, 0
	s_add_u32 s62, s62, 0x220000
	s_addc_u32 s63, s63, 0
	s_mov_b32 m0, s17
	s_add_u32 s60, s60, 0x44000
	global_load_lds_dwordx4 v194, s[68:69]
	s_mov_b32 m0, s54
	s_addc_u32 s61, s61, 0
	global_load_lds_dwordx4 v196, s[68:69]
	s_mov_b32 m0, s70
	s_and_b64 vcc, exec, s[42:43]
	global_load_lds_dwordx4 v194, s[60:61]
	s_mov_b32 m0, s71
	s_nop 0
	global_load_lds_dwordx4 v196, s[60:61]
	s_mov_b32 m0, s55
	s_nop 0
	global_load_lds_dwordx4 v194, s[62:63]
	s_mov_b32 m0, s67
	s_nop 0
	global_load_lds_dwordx4 v196, s[62:63]
	s_waitcnt lgkmcnt(0)
	s_barrier
	s_cbranch_vccnz .Lh1_558
	s_waitcnt lgkmcnt(0)
	v_mfma_f32_16x16x32_bf16 v[62:65], v[146:149], v[174:177], v[62:65]
	v_mfma_f32_16x16x32_bf16 v[58:61], v[154:157], v[174:177], v[58:61]
	v_mfma_f32_16x16x32_bf16 v[46:49], v[146:149], v[170:173], v[46:49]
	v_mfma_f32_16x16x32_bf16 v[42:45], v[154:157], v[170:173], v[42:45]
	v_mfma_f32_16x16x32_bf16 v[30:33], v[146:149], v[166:169], v[30:33]
	v_mfma_f32_16x16x32_bf16 v[26:29], v[154:157], v[166:169], v[26:29]
	v_mfma_f32_16x16x32_bf16 v[14:17], v[146:149], v[162:165], v[14:17]
	v_mfma_f32_16x16x32_bf16 v[10:13], v[154:157], v[162:165], v[10:13]
	v_mfma_f32_16x16x32_bf16 v[62:65], v[150:153], v[190:193], v[62:65]
	v_mfma_f32_16x16x32_bf16 v[58:61], v[158:161], v[190:193], v[58:61]
	v_mfma_f32_16x16x32_bf16 v[46:49], v[150:153], v[186:189], v[46:49]
	v_mfma_f32_16x16x32_bf16 v[42:45], v[158:161], v[186:189], v[42:45]
	v_mfma_f32_16x16x32_bf16 v[30:33], v[150:153], v[182:185], v[30:33]
	v_mfma_f32_16x16x32_bf16 v[26:29], v[158:161], v[182:185], v[26:29]
	v_mfma_f32_16x16x32_bf16 v[14:17], v[150:153], v[178:181], v[14:17]
	v_mfma_f32_16x16x32_bf16 v[10:13], v[158:161], v[178:181], v[10:13]
	v_mfma_f32_16x16x32_bf16 v[54:57], v[130:133], v[174:177], v[54:57]
	v_mfma_f32_16x16x32_bf16 v[50:53], v[138:141], v[174:177], v[50:53]
	v_mfma_f32_16x16x32_bf16 v[38:41], v[130:133], v[170:173], v[38:41]
	v_mfma_f32_16x16x32_bf16 v[34:37], v[138:141], v[170:173], v[34:37]
	v_mfma_f32_16x16x32_bf16 v[22:25], v[130:133], v[166:169], v[22:25]
	v_mfma_f32_16x16x32_bf16 v[18:21], v[138:141], v[166:169], v[18:21]
	v_mfma_f32_16x16x32_bf16 v[6:9], v[130:133], v[162:165], v[6:9]
	v_mfma_f32_16x16x32_bf16 v[2:5], v[138:141], v[162:165], v[2:5]
	v_mfma_f32_16x16x32_bf16 v[54:57], v[134:137], v[190:193], v[54:57]
	v_mfma_f32_16x16x32_bf16 v[50:53], v[142:145], v[190:193], v[50:53]
	v_mfma_f32_16x16x32_bf16 v[38:41], v[134:137], v[186:189], v[38:41]
	v_mfma_f32_16x16x32_bf16 v[34:37], v[142:145], v[186:189], v[34:37]
	v_mfma_f32_16x16x32_bf16 v[22:25], v[134:137], v[182:185], v[22:25]
	v_mfma_f32_16x16x32_bf16 v[18:21], v[142:145], v[182:185], v[18:21]
	v_mfma_f32_16x16x32_bf16 v[6:9], v[134:137], v[178:181], v[6:9]
	v_mfma_f32_16x16x32_bf16 v[2:5], v[142:145], v[178:181], v[2:5]
	s_setprio 0
	s_branch .Lh1_558
